# out-proj phase: converting workgroups prefetch their share of the f32 FFN weights at phase entry (LDS-DMA into spare LDS)
# baseline (speedup 1.0000x reference)
.LBB0_338:
	v_readlane_b32 s98, v254, 0
	s_cmp_lt_u32 s98, 0x80
	s_cbranch_scc1 .Lpf_done
	v_readlane_b32 s99, v255, 41
	s_cmp_eq_u32 s99, 0
	s_cbranch_scc1 .Lpf_done
	v_readlane_b32 s96, v254, 25
	v_readlane_b32 s97, v254, 26
	s_load_dwordx2 s[90:91], s[96:97], 0xe8
	s_load_dwordx2 s[96:97], s[96:97], 0x100
	v_readlane_b32 s99, v254, 29
	s_add_i32 s98, s98, 0xffffff80
	s_mul_i32 s99, s99, 0x1600000
	v_mov_b32_e32 v4, s98
	v_lshrrev_b32_e32 v2, 6, v163
	v_mul_u32_u24_e32 v4, 0x2c000, v4
	v_mul_u32_u24_e32 v2, 0x5800, v2
	v_and_b32_e32 v3, 63, v163
	v_add3_u32 v4, v4, v2, s99
	v_lshlrev_b32_e32 v3, 4, v3
	v_add_u32_e32 v2, v4, v3
	v_lshrrev_b32_e32 v4, 1, v4
	v_add_u32_e32 v3, v4, v3
	s_mov_b32 m0, 0x20000
	s_waitcnt lgkmcnt(0)
	global_load_lds_dwordx4 v2, s[90:91]
	v_add_u32_e32 v2, 0x400, v2
	global_load_lds_dwordx4 v2, s[90:91]
	v_add_u32_e32 v2, 0x400, v2
	global_load_lds_dwordx4 v2, s[90:91]
	v_add_u32_e32 v2, 0x400, v2
	global_load_lds_dwordx4 v2, s[90:91]
	v_add_u32_e32 v2, 0x400, v2
	global_load_lds_dwordx4 v2, s[90:91]
	v_add_u32_e32 v2, 0x400, v2
	global_load_lds_dwordx4 v2, s[90:91]
	v_add_u32_e32 v2, 0x400, v2
	global_load_lds_dwordx4 v2, s[90:91]
	v_add_u32_e32 v2, 0x400, v2
	global_load_lds_dwordx4 v2, s[90:91]
	v_add_u32_e32 v2, 0x400, v2
	global_load_lds_dwordx4 v2, s[90:91]
	v_add_u32_e32 v2, 0x400, v2
	global_load_lds_dwordx4 v2, s[90:91]
	v_add_u32_e32 v2, 0x400, v2
	global_load_lds_dwordx4 v2, s[90:91]
	v_add_u32_e32 v2, 0x400, v2
	global_load_lds_dwordx4 v2, s[90:91]
	v_add_u32_e32 v2, 0x400, v2
	global_load_lds_dwordx4 v2, s[90:91]
	v_add_u32_e32 v2, 0x400, v2
	global_load_lds_dwordx4 v2, s[90:91]
	v_add_u32_e32 v2, 0x400, v2
	global_load_lds_dwordx4 v2, s[90:91]
	v_add_u32_e32 v2, 0x400, v2
	global_load_lds_dwordx4 v2, s[90:91]
	v_add_u32_e32 v2, 0x400, v2
	global_load_lds_dwordx4 v2, s[90:91]
	v_add_u32_e32 v2, 0x400, v2
	global_load_lds_dwordx4 v2, s[90:91]
	v_add_u32_e32 v2, 0x400, v2
	global_load_lds_dwordx4 v2, s[90:91]
	v_add_u32_e32 v2, 0x400, v2
	global_load_lds_dwordx4 v2, s[90:91]
	v_add_u32_e32 v2, 0x400, v2
	global_load_lds_dwordx4 v2, s[90:91]
	v_add_u32_e32 v2, 0x400, v2
	global_load_lds_dwordx4 v2, s[90:91]
	v_add_u32_e32 v2, 0x400, v2
	global_load_lds_dwordx4 v3, s[96:97]
	v_add_u32_e32 v3, 0x400, v3
	global_load_lds_dwordx4 v3, s[96:97]
	v_add_u32_e32 v3, 0x400, v3
	global_load_lds_dwordx4 v3, s[96:97]
	v_add_u32_e32 v3, 0x400, v3
	global_load_lds_dwordx4 v3, s[96:97]
	v_add_u32_e32 v3, 0x400, v3
	global_load_lds_dwordx4 v3, s[96:97]
	v_add_u32_e32 v3, 0x400, v3
	global_load_lds_dwordx4 v3, s[96:97]
	v_add_u32_e32 v3, 0x400, v3
	global_load_lds_dwordx4 v3, s[96:97]
	v_add_u32_e32 v3, 0x400, v3
	global_load_lds_dwordx4 v3, s[96:97]
	v_add_u32_e32 v3, 0x400, v3
	global_load_lds_dwordx4 v3, s[96:97]
	v_add_u32_e32 v3, 0x400, v3
	global_load_lds_dwordx4 v3, s[96:97]
	v_add_u32_e32 v3, 0x400, v3
	global_load_lds_dwordx4 v3, s[96:97]
	v_add_u32_e32 v3, 0x400, v3
